# slotmap stored expert-major: each top-k unit writes one contiguous 16 KiB block instead of 4096 scattered dwords; combine gathers from 16 expert planes
# speedup vs baseline: 1.0084x; 1.0013x over previous
.LBB0_603:
	s_or_b64 exec, exec, s[4:5]
	s_mul_i32 s101, s42, 0x8800
	v_add_u32_e32 v4, s101, v4
	v_ashrrev_i32_e32 v5, 31, v4
	v_lshl_add_u64 v[4:5], v[4:5], 2, s[64:65]
	global_store_dword v[4:5], v2, off

.LBB0_617:
	s_nop 0
	v_cmp_lt_u32_e64 s[26:27], s38, v7
	v_cmp_eq_u32_e64 s[30:31], s38, v7
	v_cmp_lt_u32_e64 s[34:35], s38, v6
	v_cndmask_b32_e64 v10, 0, 1, s[26:27]
	v_cndmask_b32_e64 v17, 0, 1, s[30:31]
	v_cmp_eq_u32_e64 s[36:37], s38, v6
	v_cmp_lt_u32_e64 s[24:25], s38, v8
	v_cmp_eq_u32_e64 s[28:29], s38, v8
	v_addc_co_u32_e64 v10, vcc, 0, v10, s[34:35]
	v_addc_co_u32_e64 v11, vcc, 0, v17, s[36:37]
	v_cndmask_b32_e64 v12, 0, 1, s[24:25]
	v_cndmask_b32_e64 v16, 0, 1, s[28:29]
	v_cmp_lt_u32_e64 s[16:17], s38, v9
	v_cmp_eq_u32_e64 s[18:19], s38, v9
	v_cmp_lt_u32_e64 s[14:15], s38, v2
	v_cmp_eq_u32_e64 s[20:21], s38, v2
	v_addc_co_u32_e64 v10, vcc, v10, v12, s[16:17]
	v_addc_co_u32_e64 v11, vcc, v11, v16, s[18:19]
	v_cndmask_b32_e64 v12, 0, 1, s[14:15]
	v_cndmask_b32_e64 v13, 0, 1, s[20:21]
	v_cmp_lt_u32_e64 s[8:9], s38, v3
	v_cmp_eq_u32_e64 s[10:11], s38, v3
	v_cmp_lt_u32_e64 s[4:5], s38, v5
	v_addc_co_u32_e64 v10, vcc, v10, v12, s[8:9]
	v_addc_co_u32_e64 v11, vcc, v11, v13, s[10:11]
	v_cmp_lt_u32_e32 vcc, s38, v4
	v_cmp_eq_u32_e64 s[12:13], s38, v4
	v_add_u32_e32 v15, -2, v45
	v_cndmask_b32_e64 v14, 0, 1, vcc
	v_addc_co_u32_e64 v10, s[6:7], v10, v14, s[4:5]
	v_cndmask_b32_e64 v12, 0, 1, s[12:13]
	v_cmp_eq_u32_e64 s[6:7], s38, v5
	v_add_u32_e32 v14, -1, v45
	s_nop 0
	v_addc_co_u32_e64 v11, s[38:39], v11, v12, s[6:7]
	v_lshl_or_b32 v10, v10, 16, v11
	v_and_b32_e32 v11, 64, v45
	v_cmp_lt_i32_e64 s[38:39], v14, v11
	s_barrier
	s_nop 0
	v_cndmask_b32_e64 v14, v14, v45, s[38:39]
	v_lshlrev_b32_e32 v14, 2, v14
	ds_bpermute_b32 v14, v14, v10
	v_cmp_lt_i32_e64 s[38:39], 0, v47
	s_waitcnt lgkmcnt(0)
	s_nop 0
	v_cndmask_b32_e64 v14, 0, v14, s[38:39]
	v_cmp_lt_i32_e64 s[38:39], v15, v11
	v_add_u32_e32 v14, v14, v10
	s_nop 0
	v_cndmask_b32_e64 v15, v15, v45, s[38:39]
	v_lshlrev_b32_e32 v15, 2, v15
	ds_bpermute_b32 v15, v15, v14
	v_cmp_lt_i32_e64 s[38:39], 1, v47
	s_waitcnt lgkmcnt(0)
	s_nop 0
	v_cndmask_b32_e64 v15, 0, v15, s[38:39]
	v_add_u32_e32 v14, v15, v14
	v_add_u32_e32 v15, -4, v45
	v_cmp_lt_i32_e64 s[38:39], v15, v11
	s_nop 1
	v_cndmask_b32_e64 v15, v15, v45, s[38:39]
	v_lshlrev_b32_e32 v15, 2, v15
	ds_bpermute_b32 v15, v15, v14
	v_cmp_lt_i32_e64 s[38:39], 3, v47
	s_waitcnt lgkmcnt(0)
	s_nop 0
	v_cndmask_b32_e64 v15, 0, v15, s[38:39]
	v_add_u32_e32 v14, v15, v14
	v_add_u32_e32 v15, -8, v45
	v_cmp_lt_i32_e64 s[38:39], v15, v11
	s_nop 1
	v_cndmask_b32_e64 v15, v15, v45, s[38:39]
	v_lshlrev_b32_e32 v15, 2, v15
	ds_bpermute_b32 v15, v15, v14
	v_cmp_lt_i32_e64 s[38:39], 7, v47
	s_waitcnt lgkmcnt(0)
	s_nop 0
	v_cndmask_b32_e64 v15, 0, v15, s[38:39]
	v_add_u32_e32 v14, v15, v14
	v_add_u32_e32 v15, -16, v45
	v_cmp_lt_i32_e64 s[38:39], v15, v11
	s_nop 1
	v_cndmask_b32_e64 v15, v15, v45, s[38:39]
	v_lshlrev_b32_e32 v15, 2, v15
	ds_bpermute_b32 v15, v15, v14
	v_cmp_lt_i32_e64 s[38:39], 15, v47
	s_waitcnt lgkmcnt(0)
	s_nop 0
	v_cndmask_b32_e64 v15, 0, v15, s[38:39]
	v_add_u32_e32 v14, v15, v14
	v_subrev_u32_e32 v15, 32, v45
	v_cmp_lt_i32_e64 s[38:39], v15, v11
	s_nop 1
	v_cndmask_b32_e64 v11, v15, v45, s[38:39]
	v_lshlrev_b32_e32 v11, 2, v11
	ds_bpermute_b32 v11, v11, v14
	v_cmp_lt_i32_e64 s[38:39], 31, v47
	s_waitcnt lgkmcnt(0)
	s_nop 0
	v_cndmask_b32_e64 v11, 0, v11, s[38:39]
	v_add_u32_e32 v11, v11, v14
	v_cmp_eq_u32_e64 s[38:39], 63, v47
	s_and_saveexec_b64 s[96:97], s[38:39]
	v_mov_b32_e32 v14, s3
	ds_write_b32 v14, v11 offset:64
	s_or_b64 exec, exec, s[96:97]
	s_waitcnt lgkmcnt(0)
	s_barrier
	ds_read_b128 v[18:21], v46 offset:64
	ds_read_b128 v[22:25], v46 offset:80
	s_waitcnt lgkmcnt(0)
	s_barrier
	v_readfirstlane_b32 s33, v18
	v_readfirstlane_b32 s97, v19
	v_readfirstlane_b32 s96, v20
	v_readfirstlane_b32 s95, v21
	v_readfirstlane_b32 s79, v22
	v_readfirstlane_b32 s78, v23
	v_readfirstlane_b32 s57, v24
	v_readfirstlane_b32 s49, v25
	s_and_saveexec_b64 s[38:39], s[22:23]
	s_cbranch_execz .LBB0_651
	s_and_b64 s[22:23], s[46:47], exec
	s_cselect_b32 s76, 0, s33
	s_add_i32 s33, s97, s33
	s_and_b64 s[22:23], s[50:51], exec
	s_cselect_b32 s77, s97, 0
	s_add_i32 s33, s33, s96
	s_and_b64 s[22:23], s[58:59], exec
	s_cselect_b32 s80, s96, 0
	s_add_i32 s33, s33, s95
	s_and_b64 s[22:23], s[72:73], exec
	s_cselect_b32 s81, s95, 0
	s_add_i32 s33, s33, s79
	s_and_b64 s[22:23], s[86:87], exec
	s_cselect_b32 s79, s79, 0
	s_add_i32 s33, s33, s78
	s_and_b64 s[22:23], s[88:89], exec
	s_cselect_b32 s78, s78, 0
	s_add_i32 s33, s33, s57
	s_and_b64 s[22:23], s[90:91], exec
	s_cselect_b32 s57, s57, 0
	s_add_i32 s33, s33, s49
	s_and_b64 s[22:23], s[92:93], exec
	s_cselect_b32 s22, s49, 0
	s_add_i32 s22, s22, s57
	s_add_i32 s22, s22, s78
	s_add_i32 s22, s22, s79
	s_add_i32 s22, s22, s81
	s_add_i32 s22, s22, s80
	s_add_i32 s22, s22, s77
	v_sub_u32_e32 v10, v11, v10
	s_add_i32 s22, s22, s76
	v_add_u32_e32 v18, s22, v10
	s_ashr_i32 s22, s33, 16
	s_lshr_b32 s57, s42, 4
	s_sub_i32 s49, 32, s22
	s_lshl_b32 s22, s57, 8
	s_add_i32 s33, s22, 0x8000
	v_cmp_lt_i32_sdwa s[22:23], v18, s49 src0_sel:WORD_0 src1_sel:DWORD
	s_and_b32 s42, s94, 15
	s_and_b64 s[22:23], s[36:37], s[22:23]
	v_add_u32_e32 v14, s33, v42
	s_nor_b64 s[22:23], s[34:35], s[22:23]
	s_mul_i32 s101, s42, 0x8800
	v_add_u32_e32 v10, s101, v14
	s_and_saveexec_b64 s[78:79], s[22:23]
	s_xor_b64 s[22:23], exec, s[78:79]
	s_cbranch_execz .LBB0_622
	v_ashrrev_i32_e32 v11, 31, v10
	v_lshl_add_u64 v[10:11], v[10:11], 2, s[64:65]
	global_store_dword v[10:11], v44, off

.LBB0_624:
	s_or_b64 exec, exec, s[22:23]
	v_cndmask_b32_e64 v6, 0, 1, s[36:37]
	v_cndmask_b32_e64 v6, v6, 0, s[34:35]
	v_add_u32_sdwa v10, v18, v6 dst_sel:DWORD dst_unused:UNUSED_PAD src0_sel:WORD_0 src1_sel:DWORD
	v_cmp_gt_i32_e64 s[22:23], s49, v10
	s_and_b64 s[22:23], s[30:31], s[22:23]
	v_or_b32_e32 v11, 1, v14
	s_nor_b64 s[22:23], s[26:27], s[22:23]
	s_mul_i32 s101, s42, 0x8800
	v_add_u32_e32 v6, s101, v11
	s_and_saveexec_b64 s[30:31], s[22:23]
	s_xor_b64 s[22:23], exec, s[30:31]
	s_cbranch_execz .LBB0_626
	v_ashrrev_i32_e32 v7, 31, v6
	v_lshl_add_u64 v[6:7], v[6:7], 2, s[64:65]
	global_store_dword v[6:7], v44, off

.LBB0_628:
	s_or_b64 exec, exec, s[22:23]
	v_cndmask_b32_e64 v6, v17, 0, s[26:27]
	v_add_u32_e32 v10, v10, v6
	v_cmp_gt_i32_e64 s[22:23], s49, v10
	s_and_b64 s[22:23], s[28:29], s[22:23]
	v_or_b32_e32 v7, 2, v14
	s_nor_b64 s[22:23], s[24:25], s[22:23]
	s_mul_i32 s101, s42, 0x8800
	v_add_u32_e32 v6, s101, v7
	s_and_saveexec_b64 s[26:27], s[22:23]
	s_xor_b64 s[22:23], exec, s[26:27]
	s_cbranch_execz .LBB0_630
	v_ashrrev_i32_e32 v7, 31, v6
	v_lshl_add_u64 v[6:7], v[6:7], 2, s[64:65]
	global_store_dword v[6:7], v44, off

.LBB0_632:
	s_or_b64 exec, exec, s[22:23]
	v_cndmask_b32_e64 v6, v16, 0, s[24:25]
	v_add_u32_e32 v8, v10, v6
	v_cmp_gt_i32_e64 s[22:23], s49, v8
	s_and_b64 s[22:23], s[18:19], s[22:23]
	v_or_b32_e32 v7, 3, v14
	s_nor_b64 s[22:23], s[16:17], s[22:23]
	s_mul_i32 s101, s42, 0x8800
	v_add_u32_e32 v6, s101, v7
	s_and_saveexec_b64 s[24:25], s[22:23]
	s_xor_b64 s[22:23], exec, s[24:25]
	s_cbranch_execz .LBB0_634
	v_ashrrev_i32_e32 v7, 31, v6
	v_lshl_add_u64 v[6:7], v[6:7], 2, s[64:65]
	global_store_dword v[6:7], v44, off

.LBB0_636:
	s_or_b64 exec, exec, s[22:23]
	v_cndmask_b32_e64 v6, 0, 1, s[18:19]
	v_cndmask_b32_e64 v6, v6, 0, s[16:17]
	v_add_u32_e32 v8, v8, v6
	v_cmp_gt_i32_e64 s[16:17], s49, v8
	s_and_b64 s[16:17], s[20:21], s[16:17]
	v_or_b32_e32 v7, 4, v14
	s_nor_b64 s[16:17], s[14:15], s[16:17]
	s_mul_i32 s101, s42, 0x8800
	v_add_u32_e32 v6, s101, v7
	s_and_saveexec_b64 s[18:19], s[16:17]
	s_xor_b64 s[16:17], exec, s[18:19]
	s_cbranch_execz .LBB0_638
	v_ashrrev_i32_e32 v7, 31, v6
	v_lshl_add_u64 v[6:7], v[6:7], 2, s[64:65]
	global_store_dword v[6:7], v44, off

.LBB0_640:
	s_or_b64 exec, exec, s[16:17]
	v_cndmask_b32_e64 v2, v13, 0, s[14:15]
	v_add_u32_e32 v6, v8, v2
	v_cmp_gt_i32_e64 s[14:15], s49, v6
	s_and_b64 s[14:15], s[10:11], s[14:15]
	v_or_b32_e32 v7, 5, v14
	s_nor_b64 s[14:15], s[8:9], s[14:15]
	s_mul_i32 s101, s42, 0x8800
	v_add_u32_e32 v2, s101, v7
	s_and_saveexec_b64 s[16:17], s[14:15]
	s_xor_b64 s[14:15], exec, s[16:17]
	s_cbranch_execz .LBB0_642
	v_ashrrev_i32_e32 v3, 31, v2
	v_lshl_add_u64 v[2:3], v[2:3], 2, s[64:65]
	global_store_dword v[2:3], v44, off

.LBB0_644:
	s_or_b64 exec, exec, s[14:15]
	v_cndmask_b32_e64 v2, 0, 1, s[10:11]
	v_cndmask_b32_e64 v2, v2, 0, s[8:9]
	v_add_u32_e32 v6, v6, v2
	v_cmp_gt_i32_e64 s[8:9], s49, v6
	s_and_b64 s[8:9], s[12:13], s[8:9]
	v_or_b32_e32 v3, 6, v14
	s_nor_b64 s[8:9], vcc, s[8:9]
	s_mul_i32 s101, s42, 0x8800
	v_add_u32_e32 v2, s101, v3
	s_and_saveexec_b64 s[10:11], s[8:9]
	s_xor_b64 s[8:9], exec, s[10:11]
	s_cbranch_execz .LBB0_646
	v_ashrrev_i32_e32 v3, 31, v2
	v_lshl_add_u64 v[2:3], v[2:3], 2, s[64:65]
	global_store_dword v[2:3], v44, off

.LBB0_663:
	s_nop 0
	v_cmp_lt_u32_e64 s[26:27], s38, v7
	v_cmp_eq_u32_e64 s[30:31], s38, v7
	v_cmp_lt_u32_e64 s[34:35], s38, v6
	v_cndmask_b32_e64 v10, 0, 1, s[26:27]
	v_cndmask_b32_e64 v17, 0, 1, s[30:31]
	v_cmp_eq_u32_e64 s[36:37], s38, v6
	v_cmp_lt_u32_e64 s[24:25], s38, v8
	v_cmp_eq_u32_e64 s[28:29], s38, v8
	v_addc_co_u32_e64 v10, vcc, 0, v10, s[34:35]
	v_addc_co_u32_e64 v11, vcc, 0, v17, s[36:37]
	v_cndmask_b32_e64 v12, 0, 1, s[24:25]
	v_cndmask_b32_e64 v16, 0, 1, s[28:29]
	v_cmp_lt_u32_e64 s[16:17], s38, v9
	v_cmp_eq_u32_e64 s[18:19], s38, v9
	v_cmp_lt_u32_e64 s[14:15], s38, v2
	v_cmp_eq_u32_e64 s[20:21], s38, v2
	v_addc_co_u32_e64 v10, vcc, v10, v12, s[16:17]
	v_addc_co_u32_e64 v11, vcc, v11, v16, s[18:19]
	v_cndmask_b32_e64 v12, 0, 1, s[14:15]
	v_cndmask_b32_e64 v13, 0, 1, s[20:21]
	v_cmp_lt_u32_e64 s[8:9], s38, v3
	v_cmp_eq_u32_e64 s[10:11], s38, v3
	v_cmp_lt_u32_e64 s[4:5], s38, v5
	v_addc_co_u32_e64 v10, vcc, v10, v12, s[8:9]
	v_addc_co_u32_e64 v11, vcc, v11, v13, s[10:11]
	v_cmp_lt_u32_e32 vcc, s38, v4
	v_cmp_eq_u32_e64 s[12:13], s38, v4
	v_add_u32_e32 v15, -2, v45
	v_cndmask_b32_e64 v14, 0, 1, vcc
	v_addc_co_u32_e64 v10, s[6:7], v10, v14, s[4:5]
	v_cndmask_b32_e64 v12, 0, 1, s[12:13]
	v_cmp_eq_u32_e64 s[6:7], s38, v5
	v_add_u32_e32 v14, -1, v45
	s_nop 0
	v_addc_co_u32_e64 v11, s[38:39], v11, v12, s[6:7]
	v_lshl_or_b32 v10, v10, 16, v11
	v_and_b32_e32 v11, 64, v45
	v_cmp_lt_i32_e64 s[38:39], v14, v11
	s_barrier
	s_nop 0
	v_cndmask_b32_e64 v14, v14, v45, s[38:39]
	v_lshlrev_b32_e32 v14, 2, v14
	ds_bpermute_b32 v14, v14, v10
	v_cmp_lt_i32_e64 s[38:39], 0, v47
	s_waitcnt lgkmcnt(0)
	s_nop 0
	v_cndmask_b32_e64 v14, 0, v14, s[38:39]
	v_cmp_lt_i32_e64 s[38:39], v15, v11
	v_add_u32_e32 v14, v14, v10
	s_nop 0
	v_cndmask_b32_e64 v15, v15, v45, s[38:39]
	v_lshlrev_b32_e32 v15, 2, v15
	ds_bpermute_b32 v15, v15, v14
	v_cmp_lt_i32_e64 s[38:39], 1, v47
	s_waitcnt lgkmcnt(0)
	s_nop 0
	v_cndmask_b32_e64 v15, 0, v15, s[38:39]
	v_add_u32_e32 v14, v15, v14
	v_add_u32_e32 v15, -4, v45
	v_cmp_lt_i32_e64 s[38:39], v15, v11
	s_nop 1
	v_cndmask_b32_e64 v15, v15, v45, s[38:39]
	v_lshlrev_b32_e32 v15, 2, v15
	ds_bpermute_b32 v15, v15, v14
	v_cmp_lt_i32_e64 s[38:39], 3, v47
	s_waitcnt lgkmcnt(0)
	s_nop 0
	v_cndmask_b32_e64 v15, 0, v15, s[38:39]
	v_add_u32_e32 v14, v15, v14
	v_add_u32_e32 v15, -8, v45
	v_cmp_lt_i32_e64 s[38:39], v15, v11
	s_nop 1
	v_cndmask_b32_e64 v15, v15, v45, s[38:39]
	v_lshlrev_b32_e32 v15, 2, v15
	ds_bpermute_b32 v15, v15, v14
	v_cmp_lt_i32_e64 s[38:39], 7, v47
	s_waitcnt lgkmcnt(0)
	s_nop 0
	v_cndmask_b32_e64 v15, 0, v15, s[38:39]
	v_add_u32_e32 v14, v15, v14
	v_add_u32_e32 v15, -16, v45
	v_cmp_lt_i32_e64 s[38:39], v15, v11
	s_nop 1
	v_cndmask_b32_e64 v15, v15, v45, s[38:39]
	v_lshlrev_b32_e32 v15, 2, v15
	ds_bpermute_b32 v15, v15, v14
	v_cmp_lt_i32_e64 s[38:39], 15, v47
	s_waitcnt lgkmcnt(0)
	s_nop 0
	v_cndmask_b32_e64 v15, 0, v15, s[38:39]
	v_add_u32_e32 v14, v15, v14
	v_subrev_u32_e32 v15, 32, v45
	v_cmp_lt_i32_e64 s[38:39], v15, v11
	s_nop 1
	v_cndmask_b32_e64 v11, v15, v45, s[38:39]
	v_lshlrev_b32_e32 v11, 2, v11
	ds_bpermute_b32 v11, v11, v14
	v_cmp_lt_i32_e64 s[38:39], 31, v47
	s_waitcnt lgkmcnt(0)
	s_nop 0
	v_cndmask_b32_e64 v11, 0, v11, s[38:39]
	v_add_u32_e32 v11, v11, v14
	v_cmp_eq_u32_e64 s[38:39], 63, v47
	s_and_saveexec_b64 s[96:97], s[38:39]
	v_mov_b32_e32 v14, s3
	ds_write_b32 v14, v11 offset:64
	s_or_b64 exec, exec, s[96:97]
	s_waitcnt lgkmcnt(0)
	s_barrier
	ds_read_b128 v[18:21], v46 offset:64
	ds_read_b128 v[22:25], v46 offset:80
	s_waitcnt lgkmcnt(0)
	s_barrier
	v_readfirstlane_b32 s97, v18
	v_readfirstlane_b32 s96, v19
	v_readfirstlane_b32 s95, v20
	v_readfirstlane_b32 s79, v21
	v_readfirstlane_b32 s78, v22
	v_readfirstlane_b32 s57, v23
	v_readfirstlane_b32 s49, v24
	v_readfirstlane_b32 s42, v25
	s_and_saveexec_b64 s[38:39], s[22:23]
	s_cbranch_execz .LBB0_604
	s_and_b64 s[22:23], s[46:47], exec
	s_cselect_b32 s33, 0, s97
	s_add_i32 s76, s96, s97
	s_and_b64 s[22:23], s[50:51], exec
	s_cselect_b32 s77, s96, 0
	s_add_i32 s76, s76, s95
	s_and_b64 s[22:23], s[58:59], exec
	s_cselect_b32 s80, s95, 0
	s_add_i32 s76, s76, s79
	s_and_b64 s[22:23], s[72:73], exec
	s_cselect_b32 s79, s79, 0
	s_add_i32 s76, s76, s78
	s_and_b64 s[22:23], s[86:87], exec
	s_cselect_b32 s78, s78, 0
	s_add_i32 s76, s76, s57
	s_and_b64 s[22:23], s[88:89], exec
	s_cselect_b32 s57, s57, 0
	s_add_i32 s76, s76, s49
	s_and_b64 s[22:23], s[90:91], exec
	s_cselect_b32 s49, s49, 0
	s_add_i32 s76, s76, s42
	s_and_b64 s[22:23], s[92:93], exec
	s_cselect_b32 s22, s42, 0
	s_add_i32 s22, s22, s49
	s_add_i32 s22, s22, s57
	s_add_i32 s22, s22, s78
	s_add_i32 s22, s22, s79
	s_add_i32 s22, s22, s80
	s_add_i32 s22, s22, s77
	v_sub_u32_e32 v10, v11, v10
	s_add_i32 s22, s22, s33
	v_add_u32_e32 v18, s22, v10
	s_ashr_i32 s22, s76, 16
	s_sub_i32 s49, 0x200, s22
	s_ashr_i32 s57, s94, 4
	v_cmp_lt_i32_sdwa s[22:23], v18, s49 src0_sel:WORD_0 src1_sel:DWORD
	s_and_b32 s42, s94, 15
	s_and_b64 s[22:23], s[36:37], s[22:23]
	v_lshl_add_u32 v14, s57, 12, v42
	s_nor_b64 s[22:23], s[34:35], s[22:23]
	s_mul_i32 s101, s42, 0x8800
	v_add_u32_e32 v10, s101, v14
	s_and_saveexec_b64 s[78:79], s[22:23]
	s_xor_b64 s[22:23], exec, s[78:79]
	s_cbranch_execz .LBB0_668
	v_ashrrev_i32_e32 v11, 31, v10
	v_lshl_add_u64 v[10:11], v[10:11], 2, s[64:65]
	global_store_dword v[10:11], v44, off

.LBB0_934:
	v_lshl_add_u32 v176, s8, 2, v165
	v_mul_u32_u24_e32 v4, 0x8800, v1
	v_add_u32_e32 v4, v4, v176
	v_ashrrev_i32_e32 v5, 31, v4
	v_lshl_add_u64 v[4:5], v[4:5], 2, s[64:65]
	global_load_dword v178, v[4:5], off
	v_mov_b32_e32 v179, 0
	s_waitcnt vmcnt(0)
	v_cmp_lt_i32_e32 vcc, -1, v178
	s_and_saveexec_b64 s[4:5], vcc
	s_cbranch_execz .LBB0_936
	v_mov_b32_e32 v179, v2
	v_lshl_add_u64 v[4:5], v[178:179], 2, s[62:63]
	global_load_dword v179, v[4:5], off

.LBB0_1501:
	s_nop 0
	v_cmp_lt_u32_e64 s[26:27], s38, v7
	v_cmp_eq_u32_e64 s[30:31], s38, v7
	v_cmp_lt_u32_e64 s[34:35], s38, v6
	v_cndmask_b32_e64 v10, 0, 1, s[26:27]
	v_cndmask_b32_e64 v17, 0, 1, s[30:31]
	v_cmp_eq_u32_e64 s[36:37], s38, v6
	v_cmp_lt_u32_e64 s[24:25], s38, v8
	v_cmp_eq_u32_e64 s[28:29], s38, v8
	v_addc_co_u32_e64 v10, vcc, 0, v10, s[34:35]
	v_addc_co_u32_e64 v11, vcc, 0, v17, s[36:37]
	v_cndmask_b32_e64 v12, 0, 1, s[24:25]
	v_cndmask_b32_e64 v16, 0, 1, s[28:29]
	v_cmp_lt_u32_e64 s[16:17], s38, v9
	v_cmp_eq_u32_e64 s[18:19], s38, v9
	v_cmp_lt_u32_e64 s[14:15], s38, v2
	v_cmp_eq_u32_e64 s[20:21], s38, v2
	v_addc_co_u32_e64 v10, vcc, v10, v12, s[16:17]
	v_addc_co_u32_e64 v11, vcc, v11, v16, s[18:19]
	v_cndmask_b32_e64 v12, 0, 1, s[14:15]
	v_cndmask_b32_e64 v13, 0, 1, s[20:21]
	v_cmp_lt_u32_e64 s[8:9], s38, v3
	v_cmp_eq_u32_e64 s[10:11], s38, v3
	v_cmp_lt_u32_e64 s[4:5], s38, v5
	v_addc_co_u32_e64 v10, vcc, v10, v12, s[8:9]
	v_addc_co_u32_e64 v11, vcc, v11, v13, s[10:11]
	v_cmp_lt_u32_e32 vcc, s38, v4
	v_cmp_eq_u32_e64 s[12:13], s38, v4
	v_add_u32_e32 v15, -2, v45
	v_cndmask_b32_e64 v14, 0, 1, vcc
	v_addc_co_u32_e64 v10, s[6:7], v10, v14, s[4:5]
	v_cndmask_b32_e64 v12, 0, 1, s[12:13]
	v_cmp_eq_u32_e64 s[6:7], s38, v5
	v_add_u32_e32 v14, -1, v45
	s_nop 0
	v_addc_co_u32_e64 v11, s[38:39], v11, v12, s[6:7]
	v_lshl_or_b32 v10, v10, 16, v11
	v_and_b32_e32 v11, 64, v45
	v_cmp_lt_i32_e64 s[38:39], v14, v11
	s_barrier
	s_nop 0
	v_cndmask_b32_e64 v14, v14, v45, s[38:39]
	v_lshlrev_b32_e32 v14, 2, v14
	ds_bpermute_b32 v14, v14, v10
	v_cmp_lt_i32_e64 s[38:39], 0, v47
	s_waitcnt lgkmcnt(0)
	s_nop 0
	v_cndmask_b32_e64 v14, 0, v14, s[38:39]
	v_cmp_lt_i32_e64 s[38:39], v15, v11
	v_add_u32_e32 v14, v14, v10
	s_nop 0
	v_cndmask_b32_e64 v15, v15, v45, s[38:39]
	v_lshlrev_b32_e32 v15, 2, v15
	ds_bpermute_b32 v15, v15, v14
	v_cmp_lt_i32_e64 s[38:39], 1, v47
	s_waitcnt lgkmcnt(0)
	s_nop 0
	v_cndmask_b32_e64 v15, 0, v15, s[38:39]
	v_add_u32_e32 v14, v15, v14
	v_add_u32_e32 v15, -4, v45
	v_cmp_lt_i32_e64 s[38:39], v15, v11
	s_nop 1
	v_cndmask_b32_e64 v15, v15, v45, s[38:39]
	v_lshlrev_b32_e32 v15, 2, v15
	ds_bpermute_b32 v15, v15, v14
	v_cmp_lt_i32_e64 s[38:39], 3, v47
	s_waitcnt lgkmcnt(0)
	s_nop 0
	v_cndmask_b32_e64 v15, 0, v15, s[38:39]
	v_add_u32_e32 v14, v15, v14
	v_add_u32_e32 v15, -8, v45
	v_cmp_lt_i32_e64 s[38:39], v15, v11
	s_nop 1
	v_cndmask_b32_e64 v15, v15, v45, s[38:39]
	v_lshlrev_b32_e32 v15, 2, v15
	ds_bpermute_b32 v15, v15, v14
	v_cmp_lt_i32_e64 s[38:39], 7, v47
	s_waitcnt lgkmcnt(0)
	s_nop 0
	v_cndmask_b32_e64 v15, 0, v15, s[38:39]
	v_add_u32_e32 v14, v15, v14
	v_add_u32_e32 v15, -16, v45
	v_cmp_lt_i32_e64 s[38:39], v15, v11
	s_nop 1
	v_cndmask_b32_e64 v15, v15, v45, s[38:39]
	v_lshlrev_b32_e32 v15, 2, v15
	ds_bpermute_b32 v15, v15, v14
	v_cmp_lt_i32_e64 s[38:39], 15, v47
	s_waitcnt lgkmcnt(0)
	s_nop 0
	v_cndmask_b32_e64 v15, 0, v15, s[38:39]
	v_add_u32_e32 v14, v15, v14
	v_subrev_u32_e32 v15, 32, v45
	v_cmp_lt_i32_e64 s[38:39], v15, v11
	s_nop 1
	v_cndmask_b32_e64 v11, v15, v45, s[38:39]
	v_lshlrev_b32_e32 v11, 2, v11
	ds_bpermute_b32 v11, v11, v14
	v_cmp_lt_i32_e64 s[38:39], 31, v47
	s_waitcnt lgkmcnt(0)
	s_nop 0
	v_cndmask_b32_e64 v11, 0, v11, s[38:39]
	v_add_u32_e32 v11, v11, v14
	v_cmp_eq_u32_e64 s[38:39], 63, v47
	s_and_saveexec_b64 s[96:97], s[38:39]
	v_mov_b32_e32 v14, s3
	ds_write_b32 v14, v11 offset:64
	s_or_b64 exec, exec, s[96:97]
	s_waitcnt lgkmcnt(0)
	s_barrier
	ds_read_b128 v[18:21], v46 offset:64
	ds_read_b128 v[22:25], v46 offset:80
	s_waitcnt lgkmcnt(0)
	s_barrier
	v_readfirstlane_b32 s33, v18
	v_readfirstlane_b32 s97, v19
	v_readfirstlane_b32 s96, v20
	v_readfirstlane_b32 s95, v21
	v_readfirstlane_b32 s79, v22
	v_readfirstlane_b32 s78, v23
	v_readfirstlane_b32 s57, v24
	v_readfirstlane_b32 s49, v25
	s_and_saveexec_b64 s[38:39], s[22:23]
	s_cbranch_execz .LBB0_1535
	s_and_b64 s[22:23], s[46:47], exec
	s_cselect_b32 s76, 0, s33
	s_add_i32 s33, s97, s33
	s_and_b64 s[22:23], s[58:59], exec
	s_cselect_b32 s77, s97, 0
	s_add_i32 s33, s33, s96
	s_and_b64 s[22:23], s[72:73], exec
	s_cselect_b32 s80, s96, 0
	s_add_i32 s33, s33, s95
	s_and_b64 s[22:23], s[84:85], exec
	s_cselect_b32 s81, s95, 0
	s_add_i32 s33, s33, s79
	s_and_b64 s[22:23], s[86:87], exec
	s_cselect_b32 s79, s79, 0
	s_add_i32 s33, s33, s78
	s_and_b64 s[22:23], s[88:89], exec
	s_cselect_b32 s78, s78, 0
	s_add_i32 s33, s33, s57
	s_and_b64 s[22:23], s[90:91], exec
	s_cselect_b32 s57, s57, 0
	s_add_i32 s33, s33, s49
	s_and_b64 s[22:23], s[92:93], exec
	s_cselect_b32 s22, s49, 0
	s_add_i32 s22, s22, s57
	s_add_i32 s22, s22, s78
	s_add_i32 s22, s22, s79
	s_add_i32 s22, s22, s81
	s_add_i32 s22, s22, s80
	s_add_i32 s22, s22, s77
	v_sub_u32_e32 v10, v11, v10
	s_add_i32 s22, s22, s76
	v_add_u32_e32 v18, s22, v10
	s_ashr_i32 s22, s33, 16
	s_lshr_b32 s57, s42, 4
	s_sub_i32 s49, 32, s22
	s_lshl_b32 s22, s57, 8
	s_add_i32 s33, s22, 0x8000
	v_cmp_lt_i32_sdwa s[22:23], v18, s49 src0_sel:WORD_0 src1_sel:DWORD
	s_and_b32 s42, s94, 15
	s_and_b64 s[22:23], s[36:37], s[22:23]
	v_add_u32_e32 v14, s33, v42
	s_nor_b64 s[22:23], s[34:35], s[22:23]
	s_mul_i32 s101, s42, 0x8800
	v_add_u32_e32 v10, s101, v14
	s_and_saveexec_b64 s[76:77], s[22:23]
	s_xor_b64 s[22:23], exec, s[76:77]
	s_cbranch_execz .LBB0_1506
	v_ashrrev_i32_e32 v11, 31, v10
	v_lshl_add_u64 v[10:11], v[10:11], 2, s[64:65]
	global_store_dword v[10:11], v44, off

.LBB0_1547:
	s_nop 0
	v_cmp_lt_u32_e64 s[26:27], s38, v7
	v_cmp_eq_u32_e64 s[30:31], s38, v7
	v_cmp_lt_u32_e64 s[34:35], s38, v6
	v_cndmask_b32_e64 v10, 0, 1, s[26:27]
	v_cndmask_b32_e64 v17, 0, 1, s[30:31]
	v_cmp_eq_u32_e64 s[36:37], s38, v6
	v_cmp_lt_u32_e64 s[24:25], s38, v8
	v_cmp_eq_u32_e64 s[28:29], s38, v8
	v_addc_co_u32_e64 v10, vcc, 0, v10, s[34:35]
	v_addc_co_u32_e64 v11, vcc, 0, v17, s[36:37]
	v_cndmask_b32_e64 v12, 0, 1, s[24:25]
	v_cndmask_b32_e64 v16, 0, 1, s[28:29]
	v_cmp_lt_u32_e64 s[16:17], s38, v9
	v_cmp_eq_u32_e64 s[18:19], s38, v9
	v_cmp_lt_u32_e64 s[14:15], s38, v2
	v_cmp_eq_u32_e64 s[20:21], s38, v2
	v_addc_co_u32_e64 v10, vcc, v10, v12, s[16:17]
	v_addc_co_u32_e64 v11, vcc, v11, v16, s[18:19]
	v_cndmask_b32_e64 v12, 0, 1, s[14:15]
	v_cndmask_b32_e64 v13, 0, 1, s[20:21]
	v_cmp_lt_u32_e64 s[8:9], s38, v3
	v_cmp_eq_u32_e64 s[10:11], s38, v3
	v_cmp_lt_u32_e64 s[4:5], s38, v5
	v_addc_co_u32_e64 v10, vcc, v10, v12, s[8:9]
	v_addc_co_u32_e64 v11, vcc, v11, v13, s[10:11]
	v_cmp_lt_u32_e32 vcc, s38, v4
	v_cmp_eq_u32_e64 s[12:13], s38, v4
	v_add_u32_e32 v15, -2, v45
	v_cndmask_b32_e64 v14, 0, 1, vcc
	v_addc_co_u32_e64 v10, s[6:7], v10, v14, s[4:5]
	v_cndmask_b32_e64 v12, 0, 1, s[12:13]
	v_cmp_eq_u32_e64 s[6:7], s38, v5
	v_add_u32_e32 v14, -1, v45
	s_nop 0
	v_addc_co_u32_e64 v11, s[38:39], v11, v12, s[6:7]
	v_lshl_or_b32 v10, v10, 16, v11
	v_and_b32_e32 v11, 64, v45
	v_cmp_lt_i32_e64 s[38:39], v14, v11
	s_barrier
	s_nop 0
	v_cndmask_b32_e64 v14, v14, v45, s[38:39]
	v_lshlrev_b32_e32 v14, 2, v14
	ds_bpermute_b32 v14, v14, v10
	v_cmp_lt_i32_e64 s[38:39], 0, v47
	s_waitcnt lgkmcnt(0)
	s_nop 0
	v_cndmask_b32_e64 v14, 0, v14, s[38:39]
	v_cmp_lt_i32_e64 s[38:39], v15, v11
	v_add_u32_e32 v14, v14, v10
	s_nop 0
	v_cndmask_b32_e64 v15, v15, v45, s[38:39]
	v_lshlrev_b32_e32 v15, 2, v15
	ds_bpermute_b32 v15, v15, v14
	v_cmp_lt_i32_e64 s[38:39], 1, v47
	s_waitcnt lgkmcnt(0)
	s_nop 0
	v_cndmask_b32_e64 v15, 0, v15, s[38:39]
	v_add_u32_e32 v14, v15, v14
	v_add_u32_e32 v15, -4, v45
	v_cmp_lt_i32_e64 s[38:39], v15, v11
	s_nop 1
	v_cndmask_b32_e64 v15, v15, v45, s[38:39]
	v_lshlrev_b32_e32 v15, 2, v15
	ds_bpermute_b32 v15, v15, v14
	v_cmp_lt_i32_e64 s[38:39], 3, v47
	s_waitcnt lgkmcnt(0)
	s_nop 0
	v_cndmask_b32_e64 v15, 0, v15, s[38:39]
	v_add_u32_e32 v14, v15, v14
	v_add_u32_e32 v15, -8, v45
	v_cmp_lt_i32_e64 s[38:39], v15, v11
	s_nop 1
	v_cndmask_b32_e64 v15, v15, v45, s[38:39]
	v_lshlrev_b32_e32 v15, 2, v15
	ds_bpermute_b32 v15, v15, v14
	v_cmp_lt_i32_e64 s[38:39], 7, v47
	s_waitcnt lgkmcnt(0)
	s_nop 0
	v_cndmask_b32_e64 v15, 0, v15, s[38:39]
	v_add_u32_e32 v14, v15, v14
	v_add_u32_e32 v15, -16, v45
	v_cmp_lt_i32_e64 s[38:39], v15, v11
	s_nop 1
	v_cndmask_b32_e64 v15, v15, v45, s[38:39]
	v_lshlrev_b32_e32 v15, 2, v15
	ds_bpermute_b32 v15, v15, v14
	v_cmp_lt_i32_e64 s[38:39], 15, v47
	s_waitcnt lgkmcnt(0)
	s_nop 0
	v_cndmask_b32_e64 v15, 0, v15, s[38:39]
	v_add_u32_e32 v14, v15, v14
	v_subrev_u32_e32 v15, 32, v45
	v_cmp_lt_i32_e64 s[38:39], v15, v11
	s_nop 1
	v_cndmask_b32_e64 v11, v15, v45, s[38:39]
	v_lshlrev_b32_e32 v11, 2, v11
	ds_bpermute_b32 v11, v11, v14
	v_cmp_lt_i32_e64 s[38:39], 31, v47
	s_waitcnt lgkmcnt(0)
	s_nop 0
	v_cndmask_b32_e64 v11, 0, v11, s[38:39]
	v_add_u32_e32 v11, v11, v14
	v_cmp_eq_u32_e64 s[38:39], 63, v47
	s_and_saveexec_b64 s[96:97], s[38:39]
	v_mov_b32_e32 v14, s3
	ds_write_b32 v14, v11 offset:64
	s_or_b64 exec, exec, s[96:97]
	s_waitcnt lgkmcnt(0)
	s_barrier
	ds_read_b128 v[18:21], v46 offset:64
	ds_read_b128 v[22:25], v46 offset:80
	s_waitcnt lgkmcnt(0)
	s_barrier
	v_readfirstlane_b32 s33, v18
	v_readfirstlane_b32 s96, v19
	v_readfirstlane_b32 s95, v20
	v_readfirstlane_b32 s79, v21
	v_readfirstlane_b32 s78, v22
	v_readfirstlane_b32 s57, v23
	v_readfirstlane_b32 s49, v24
	v_readfirstlane_b32 s42, v25
	s_and_saveexec_b64 s[38:39], s[22:23]
	s_cbranch_execz .LBB0_1488
	s_and_b64 s[22:23], s[46:47], exec
	s_cselect_b32 s76, 0, s33
	s_add_i32 s33, s96, s33
	s_and_b64 s[22:23], s[58:59], exec
	s_cselect_b32 s77, s96, 0
	s_add_i32 s33, s33, s95
	s_and_b64 s[22:23], s[72:73], exec
	s_cselect_b32 s80, s95, 0
	s_add_i32 s33, s33, s79
	s_and_b64 s[22:23], s[84:85], exec
	s_cselect_b32 s79, s79, 0
	s_add_i32 s33, s33, s78
	s_and_b64 s[22:23], s[86:87], exec
	s_cselect_b32 s78, s78, 0
	s_add_i32 s33, s33, s57
	s_and_b64 s[22:23], s[88:89], exec
	s_cselect_b32 s57, s57, 0
	s_add_i32 s33, s33, s49
	s_and_b64 s[22:23], s[90:91], exec
	s_cselect_b32 s49, s49, 0
	s_add_i32 s33, s33, s42
	s_and_b64 s[22:23], s[92:93], exec
	s_cselect_b32 s22, s42, 0
	s_add_i32 s22, s22, s49
	s_add_i32 s22, s22, s57
	s_add_i32 s22, s22, s78
	s_add_i32 s22, s22, s79
	s_add_i32 s22, s22, s80
	s_add_i32 s22, s22, s77
	v_sub_u32_e32 v10, v11, v10
	s_add_i32 s22, s22, s76
	v_add_u32_e32 v18, s22, v10
	s_ashr_i32 s22, s33, 16
	s_sub_i32 s49, 0x200, s22
	s_ashr_i32 s57, s94, 4
	v_cmp_lt_i32_sdwa s[22:23], v18, s49 src0_sel:WORD_0 src1_sel:DWORD
	s_and_b32 s42, s94, 15
	s_and_b64 s[22:23], s[36:37], s[22:23]
	v_lshl_add_u32 v14, s57, 12, v42
	s_nor_b64 s[22:23], s[34:35], s[22:23]
	s_mul_i32 s101, s42, 0x8800
	v_add_u32_e32 v10, s101, v14
	s_and_saveexec_b64 s[76:77], s[22:23]
	s_xor_b64 s[22:23], exec, s[76:77]
	s_cbranch_execz .LBB0_1552
	v_ashrrev_i32_e32 v11, 31, v10
	v_lshl_add_u64 v[10:11], v[10:11], 2, s[64:65]
	global_store_dword v[10:11], v44, off

.LBB0_2304:
	s_or_b64 exec, exec, s[4:5]
	s_mul_i32 s101, s49, 0x8800
	v_add_u32_e32 v4, s101, v4
	v_ashrrev_i32_e32 v5, 31, v4
	v_lshl_add_u64 v[4:5], v[4:5], 2, s[64:65]
	global_store_dword v[4:5], v2, off

.LBB0_2316:
	s_nop 0
	v_cmp_lt_u32_e64 s[26:27], s38, v7
	v_cmp_eq_u32_e64 s[30:31], s38, v7
	v_cmp_lt_u32_e64 s[34:35], s38, v6
	v_cndmask_b32_e64 v10, 0, 1, s[26:27]
	v_cndmask_b32_e64 v17, 0, 1, s[30:31]
	v_cmp_eq_u32_e64 s[36:37], s38, v6
	v_cmp_lt_u32_e64 s[24:25], s38, v8
	v_cmp_eq_u32_e64 s[28:29], s38, v8
	v_addc_co_u32_e64 v10, vcc, 0, v10, s[34:35]
	v_addc_co_u32_e64 v11, vcc, 0, v17, s[36:37]
	v_cndmask_b32_e64 v12, 0, 1, s[24:25]
	v_cndmask_b32_e64 v16, 0, 1, s[28:29]
	v_cmp_lt_u32_e64 s[16:17], s38, v9
	v_cmp_eq_u32_e64 s[18:19], s38, v9
	v_cmp_lt_u32_e64 s[14:15], s38, v2
	v_cmp_eq_u32_e64 s[20:21], s38, v2
	v_addc_co_u32_e64 v10, vcc, v10, v12, s[16:17]
	v_addc_co_u32_e64 v11, vcc, v11, v16, s[18:19]
	v_cndmask_b32_e64 v12, 0, 1, s[14:15]
	v_cndmask_b32_e64 v13, 0, 1, s[20:21]
	v_cmp_lt_u32_e64 s[8:9], s38, v3
	v_cmp_eq_u32_e64 s[10:11], s38, v3
	v_cmp_lt_u32_e64 s[4:5], s38, v5
	v_addc_co_u32_e64 v10, vcc, v10, v12, s[8:9]
	v_addc_co_u32_e64 v11, vcc, v11, v13, s[10:11]
	v_cmp_lt_u32_e32 vcc, s38, v4
	v_cmp_eq_u32_e64 s[12:13], s38, v4
	v_add_u32_e32 v15, -2, v44
	v_cndmask_b32_e64 v14, 0, 1, vcc
	v_addc_co_u32_e64 v10, s[6:7], v10, v14, s[4:5]
	v_cndmask_b32_e64 v12, 0, 1, s[12:13]
	v_cmp_eq_u32_e64 s[6:7], s38, v5
	v_add_u32_e32 v14, -1, v44
	s_nop 0
	v_addc_co_u32_e64 v11, s[38:39], v11, v12, s[6:7]
	v_lshl_or_b32 v10, v10, 16, v11
	v_and_b32_e32 v11, 64, v44
	v_cmp_lt_i32_e64 s[38:39], v14, v11
	s_barrier
	s_nop 0
	v_cndmask_b32_e64 v14, v14, v44, s[38:39]
	v_lshlrev_b32_e32 v14, 2, v14
	ds_bpermute_b32 v14, v14, v10
	v_cmp_lt_i32_e64 s[38:39], 0, v47
	s_waitcnt lgkmcnt(0)
	s_nop 0
	v_cndmask_b32_e64 v14, 0, v14, s[38:39]
	v_cmp_lt_i32_e64 s[38:39], v15, v11
	v_add_u32_e32 v14, v14, v10
	s_nop 0
	v_cndmask_b32_e64 v15, v15, v44, s[38:39]
	v_lshlrev_b32_e32 v15, 2, v15
	ds_bpermute_b32 v15, v15, v14
	v_cmp_lt_i32_e64 s[38:39], 1, v47
	s_waitcnt lgkmcnt(0)
	s_nop 0
	v_cndmask_b32_e64 v15, 0, v15, s[38:39]
	v_add_u32_e32 v14, v15, v14
	v_add_u32_e32 v15, -4, v44
	v_cmp_lt_i32_e64 s[38:39], v15, v11
	s_nop 1
	v_cndmask_b32_e64 v15, v15, v44, s[38:39]
	v_lshlrev_b32_e32 v15, 2, v15
	ds_bpermute_b32 v15, v15, v14
	v_cmp_lt_i32_e64 s[38:39], 3, v47
	s_waitcnt lgkmcnt(0)
	s_nop 0
	v_cndmask_b32_e64 v15, 0, v15, s[38:39]
	v_add_u32_e32 v14, v15, v14
	v_add_u32_e32 v15, -8, v44
	v_cmp_lt_i32_e64 s[38:39], v15, v11
	s_nop 1
	v_cndmask_b32_e64 v15, v15, v44, s[38:39]
	v_lshlrev_b32_e32 v15, 2, v15
	ds_bpermute_b32 v15, v15, v14
	v_cmp_lt_i32_e64 s[38:39], 7, v47
	s_waitcnt lgkmcnt(0)
	s_nop 0
	v_cndmask_b32_e64 v15, 0, v15, s[38:39]
	v_add_u32_e32 v14, v15, v14
	v_add_u32_e32 v15, -16, v44
	v_cmp_lt_i32_e64 s[38:39], v15, v11
	s_nop 1
	v_cndmask_b32_e64 v15, v15, v44, s[38:39]
	v_lshlrev_b32_e32 v15, 2, v15
	ds_bpermute_b32 v15, v15, v14
	v_cmp_lt_i32_e64 s[38:39], 15, v47
	s_waitcnt lgkmcnt(0)
	s_nop 0
	v_cndmask_b32_e64 v15, 0, v15, s[38:39]
	v_add_u32_e32 v14, v15, v14
	v_subrev_u32_e32 v15, 32, v44
	v_cmp_lt_i32_e64 s[38:39], v15, v11
	s_nop 1
	v_cndmask_b32_e64 v11, v15, v44, s[38:39]
	v_lshlrev_b32_e32 v11, 2, v11
	ds_bpermute_b32 v11, v11, v14
	v_cmp_lt_i32_e64 s[38:39], 31, v47
	s_waitcnt lgkmcnt(0)
	s_nop 0
	v_cndmask_b32_e64 v11, 0, v11, s[38:39]
	v_add_u32_e32 v11, v11, v14
	v_cmp_eq_u32_e64 s[38:39], 63, v47
	s_and_saveexec_b64 s[94:95], s[38:39]
	v_mov_b32_e32 v14, s3
	ds_write_b32 v14, v11 offset:64
	s_or_b64 exec, exec, s[94:95]
	s_waitcnt lgkmcnt(0)
	s_barrier
	ds_read_b128 v[18:21], v46 offset:64
	ds_read_b128 v[22:25], v46 offset:80
	s_waitcnt lgkmcnt(0)
	s_barrier
	v_readfirstlane_b32 s33, v18
	v_readfirstlane_b32 s95, v19
	v_readfirstlane_b32 s94, v20
	v_readfirstlane_b32 s93, v21
	v_readfirstlane_b32 s79, v22
	v_readfirstlane_b32 s78, v23
	v_readfirstlane_b32 s57, v24
	v_readfirstlane_b32 s49, v25
	s_and_saveexec_b64 s[38:39], s[22:23]
	s_cbranch_execz .LBB0_2305
	s_and_b64 s[22:23], s[42:43], exec
	s_cselect_b32 s76, 0, s33
	s_add_i32 s33, s95, s33
	s_and_b64 s[22:23], s[46:47], exec
	s_cselect_b32 s77, s95, 0
	s_add_i32 s33, s33, s94
	s_and_b64 s[22:23], s[58:59], exec
	s_cselect_b32 s80, s94, 0
	s_add_i32 s33, s33, s93
	s_and_b64 s[22:23], s[72:73], exec
	s_cselect_b32 s81, s93, 0
	s_add_i32 s33, s33, s79
	s_and_b64 s[22:23], s[84:85], exec
	s_cselect_b32 s79, s79, 0
	s_add_i32 s33, s33, s78
	s_and_b64 s[22:23], s[86:87], exec
	s_cselect_b32 s78, s78, 0
	s_add_i32 s33, s33, s57
	s_and_b64 s[22:23], s[88:89], exec
	s_cselect_b32 s57, s57, 0
	s_add_i32 s33, s33, s49
	s_and_b64 s[22:23], s[90:91], exec
	s_cselect_b32 s22, s49, 0
	s_add_i32 s22, s22, s57
	s_add_i32 s22, s22, s78
	s_add_i32 s22, s22, s79
	s_add_i32 s22, s22, s81
	s_add_i32 s22, s22, s80
	s_add_i32 s22, s22, s77
	v_sub_u32_e32 v10, v11, v10
	s_add_i32 s22, s22, s76
	v_add_u32_e32 v18, s22, v10
	s_ashr_i32 s22, s33, 16
	s_sub_i32 s57, 0x200, s22
	s_ashr_i32 s78, s92, 4
	v_cmp_lt_i32_sdwa s[22:23], v18, s57 src0_sel:WORD_0 src1_sel:DWORD
	s_and_b32 s49, s92, 15
	s_and_b64 s[22:23], s[36:37], s[22:23]
	v_lshl_add_u32 v14, s78, 12, v42
	s_nor_b64 s[22:23], s[34:35], s[22:23]
	s_mul_i32 s101, s49, 0x8800
	v_add_u32_e32 v10, s101, v14
	s_and_saveexec_b64 s[76:77], s[22:23]
	s_xor_b64 s[22:23], exec, s[76:77]
	s_cbranch_execz .LBB0_2321
	v_ashrrev_i32_e32 v11, 31, v10
	v_lshl_add_u64 v[10:11], v[10:11], 2, s[64:65]
	global_store_dword v[10:11], v45, off

.LBB0_2323:
	s_or_b64 exec, exec, s[22:23]
	v_cndmask_b32_e64 v6, 0, 1, s[36:37]
	v_cndmask_b32_e64 v6, v6, 0, s[34:35]
	v_add_u32_sdwa v10, v18, v6 dst_sel:DWORD dst_unused:UNUSED_PAD src0_sel:WORD_0 src1_sel:DWORD
	v_cmp_gt_i32_e64 s[22:23], s57, v10
	s_and_b64 s[22:23], s[30:31], s[22:23]
	v_or_b32_e32 v11, 1, v14
	s_nor_b64 s[22:23], s[26:27], s[22:23]
	s_mul_i32 s101, s49, 0x8800
	v_add_u32_e32 v6, s101, v11
	s_and_saveexec_b64 s[30:31], s[22:23]
	s_xor_b64 s[22:23], exec, s[30:31]
	s_cbranch_execz .LBB0_2325
	v_ashrrev_i32_e32 v7, 31, v6
	v_lshl_add_u64 v[6:7], v[6:7], 2, s[64:65]
	global_store_dword v[6:7], v45, off

.LBB0_2327:
	s_or_b64 exec, exec, s[22:23]
	v_cndmask_b32_e64 v6, v17, 0, s[26:27]
	v_add_u32_e32 v10, v10, v6
	v_cmp_gt_i32_e64 s[22:23], s57, v10
	s_and_b64 s[22:23], s[28:29], s[22:23]
	v_or_b32_e32 v7, 2, v14
	s_nor_b64 s[22:23], s[24:25], s[22:23]
	s_mul_i32 s101, s49, 0x8800
	v_add_u32_e32 v6, s101, v7
	s_and_saveexec_b64 s[26:27], s[22:23]
	s_xor_b64 s[22:23], exec, s[26:27]
	s_cbranch_execz .LBB0_2329
	v_ashrrev_i32_e32 v7, 31, v6
	v_lshl_add_u64 v[6:7], v[6:7], 2, s[64:65]
	global_store_dword v[6:7], v45, off

.LBB0_2331:
	s_or_b64 exec, exec, s[22:23]
	v_cndmask_b32_e64 v6, v16, 0, s[24:25]
	v_add_u32_e32 v8, v10, v6
	v_cmp_gt_i32_e64 s[22:23], s57, v8
	s_and_b64 s[22:23], s[18:19], s[22:23]
	v_or_b32_e32 v7, 3, v14
	s_nor_b64 s[22:23], s[16:17], s[22:23]
	s_mul_i32 s101, s49, 0x8800
	v_add_u32_e32 v6, s101, v7
	s_and_saveexec_b64 s[24:25], s[22:23]
	s_xor_b64 s[22:23], exec, s[24:25]
	s_cbranch_execz .LBB0_2333
	v_ashrrev_i32_e32 v7, 31, v6
	v_lshl_add_u64 v[6:7], v[6:7], 2, s[64:65]
	global_store_dword v[6:7], v45, off

.LBB0_2335:
	s_or_b64 exec, exec, s[22:23]
	v_cndmask_b32_e64 v6, 0, 1, s[18:19]
	v_cndmask_b32_e64 v6, v6, 0, s[16:17]
	v_add_u32_e32 v8, v8, v6
	v_cmp_gt_i32_e64 s[16:17], s57, v8
	s_and_b64 s[16:17], s[20:21], s[16:17]
	v_or_b32_e32 v7, 4, v14
	s_nor_b64 s[16:17], s[14:15], s[16:17]
	s_mul_i32 s101, s49, 0x8800
	v_add_u32_e32 v6, s101, v7
	s_and_saveexec_b64 s[18:19], s[16:17]
	s_xor_b64 s[16:17], exec, s[18:19]
	s_cbranch_execz .LBB0_2337
	v_ashrrev_i32_e32 v7, 31, v6
	v_lshl_add_u64 v[6:7], v[6:7], 2, s[64:65]
	global_store_dword v[6:7], v45, off

.LBB0_2339:
	s_or_b64 exec, exec, s[16:17]
	v_cndmask_b32_e64 v2, v13, 0, s[14:15]
	v_add_u32_e32 v6, v8, v2
	v_cmp_gt_i32_e64 s[14:15], s57, v6
	s_and_b64 s[14:15], s[10:11], s[14:15]
	v_or_b32_e32 v7, 5, v14
	s_nor_b64 s[14:15], s[8:9], s[14:15]
	s_mul_i32 s101, s49, 0x8800
	v_add_u32_e32 v2, s101, v7
	s_and_saveexec_b64 s[16:17], s[14:15]
	s_xor_b64 s[14:15], exec, s[16:17]
	s_cbranch_execz .LBB0_2341
	v_ashrrev_i32_e32 v3, 31, v2
	v_lshl_add_u64 v[2:3], v[2:3], 2, s[64:65]
	global_store_dword v[2:3], v45, off

.LBB0_2343:
	s_or_b64 exec, exec, s[14:15]
	v_cndmask_b32_e64 v2, 0, 1, s[10:11]
	v_cndmask_b32_e64 v2, v2, 0, s[8:9]
	v_add_u32_e32 v6, v6, v2
	v_cmp_gt_i32_e64 s[8:9], s57, v6
	s_and_b64 s[8:9], s[12:13], s[8:9]
	v_or_b32_e32 v3, 6, v14
	s_nor_b64 s[8:9], vcc, s[8:9]
	s_mul_i32 s101, s49, 0x8800
	v_add_u32_e32 v2, s101, v3
	s_and_saveexec_b64 s[10:11], s[8:9]
	s_xor_b64 s[8:9], exec, s[10:11]
	s_cbranch_execz .LBB0_2345
	v_ashrrev_i32_e32 v3, 31, v2
	v_lshl_add_u64 v[2:3], v[2:3], 2, s[64:65]
	global_store_dword v[2:3], v45, off

.LBB0_2980:
	s_or_b64 exec, exec, s[4:5]
	s_mul_i32 s101, s57, 0x8800
	v_add_u32_e32 v4, s101, v4
	v_ashrrev_i32_e32 v5, 31, v4
	v_lshl_add_u64 v[4:5], v[4:5], 2, s[64:65]
	global_store_dword v[4:5], v2, off

.LBB0_2992:
	s_nop 0
	v_cmp_lt_u32_e64 s[26:27], s38, v7
	v_cmp_eq_u32_e64 s[30:31], s38, v7
	v_cmp_lt_u32_e64 s[34:35], s38, v6
	v_cndmask_b32_e64 v10, 0, 1, s[26:27]
	v_cndmask_b32_e64 v17, 0, 1, s[30:31]
	v_cmp_eq_u32_e64 s[36:37], s38, v6
	v_cmp_lt_u32_e64 s[24:25], s38, v8
	v_cmp_eq_u32_e64 s[28:29], s38, v8
	v_addc_co_u32_e64 v10, vcc, 0, v10, s[34:35]
	v_addc_co_u32_e64 v11, vcc, 0, v17, s[36:37]
	v_cndmask_b32_e64 v12, 0, 1, s[24:25]
	v_cndmask_b32_e64 v16, 0, 1, s[28:29]
	v_cmp_lt_u32_e64 s[16:17], s38, v9
	v_cmp_eq_u32_e64 s[18:19], s38, v9
	v_cmp_lt_u32_e64 s[14:15], s38, v2
	v_cmp_eq_u32_e64 s[20:21], s38, v2
	v_addc_co_u32_e64 v10, vcc, v10, v12, s[16:17]
	v_addc_co_u32_e64 v11, vcc, v11, v16, s[18:19]
	v_cndmask_b32_e64 v12, 0, 1, s[14:15]
	v_cndmask_b32_e64 v13, 0, 1, s[20:21]
	v_cmp_lt_u32_e64 s[8:9], s38, v3
	v_cmp_eq_u32_e64 s[10:11], s38, v3
	v_cmp_lt_u32_e64 s[4:5], s38, v5
	v_addc_co_u32_e64 v10, vcc, v10, v12, s[8:9]
	v_addc_co_u32_e64 v11, vcc, v11, v13, s[10:11]
	v_cmp_lt_u32_e32 vcc, s38, v4
	v_cmp_eq_u32_e64 s[12:13], s38, v4
	v_add_u32_e32 v15, -2, v44
	v_cndmask_b32_e64 v14, 0, 1, vcc
	v_addc_co_u32_e64 v10, s[6:7], v10, v14, s[4:5]
	v_cndmask_b32_e64 v12, 0, 1, s[12:13]
	v_cmp_eq_u32_e64 s[6:7], s38, v5
	v_add_u32_e32 v14, -1, v44
	s_nop 0
	v_addc_co_u32_e64 v11, s[38:39], v11, v12, s[6:7]
	v_lshl_or_b32 v10, v10, 16, v11
	v_and_b32_e32 v11, 64, v44
	v_cmp_lt_i32_e64 s[38:39], v14, v11
	s_barrier
	s_nop 0
	v_cndmask_b32_e64 v14, v14, v44, s[38:39]
	v_lshlrev_b32_e32 v14, 2, v14
	ds_bpermute_b32 v14, v14, v10
	v_cmp_lt_i32_e64 s[38:39], 0, v47
	s_waitcnt lgkmcnt(0)
	s_nop 0
	v_cndmask_b32_e64 v14, 0, v14, s[38:39]
	v_cmp_lt_i32_e64 s[38:39], v15, v11
	v_add_u32_e32 v14, v14, v10
	s_nop 0
	v_cndmask_b32_e64 v15, v15, v44, s[38:39]
	v_lshlrev_b32_e32 v15, 2, v15
	ds_bpermute_b32 v15, v15, v14
	v_cmp_lt_i32_e64 s[38:39], 1, v47
	s_waitcnt lgkmcnt(0)
	s_nop 0
	v_cndmask_b32_e64 v15, 0, v15, s[38:39]
	v_add_u32_e32 v14, v15, v14
	v_add_u32_e32 v15, -4, v44
	v_cmp_lt_i32_e64 s[38:39], v15, v11
	s_nop 1
	v_cndmask_b32_e64 v15, v15, v44, s[38:39]
	v_lshlrev_b32_e32 v15, 2, v15
	ds_bpermute_b32 v15, v15, v14
	v_cmp_lt_i32_e64 s[38:39], 3, v47
	s_waitcnt lgkmcnt(0)
	s_nop 0
	v_cndmask_b32_e64 v15, 0, v15, s[38:39]
	v_add_u32_e32 v14, v15, v14
	v_add_u32_e32 v15, -8, v44
	v_cmp_lt_i32_e64 s[38:39], v15, v11
	s_nop 1
	v_cndmask_b32_e64 v15, v15, v44, s[38:39]
	v_lshlrev_b32_e32 v15, 2, v15
	ds_bpermute_b32 v15, v15, v14
	v_cmp_lt_i32_e64 s[38:39], 7, v47
	s_waitcnt lgkmcnt(0)
	s_nop 0
	v_cndmask_b32_e64 v15, 0, v15, s[38:39]
	v_add_u32_e32 v14, v15, v14
	v_add_u32_e32 v15, -16, v44
	v_cmp_lt_i32_e64 s[38:39], v15, v11
	s_nop 1
	v_cndmask_b32_e64 v15, v15, v44, s[38:39]
	v_lshlrev_b32_e32 v15, 2, v15
	ds_bpermute_b32 v15, v15, v14
	v_cmp_lt_i32_e64 s[38:39], 15, v47
	s_waitcnt lgkmcnt(0)
	s_nop 0
	v_cndmask_b32_e64 v15, 0, v15, s[38:39]
	v_add_u32_e32 v14, v15, v14
	v_subrev_u32_e32 v15, 32, v44
	v_cmp_lt_i32_e64 s[38:39], v15, v11
	s_nop 1
	v_cndmask_b32_e64 v11, v15, v44, s[38:39]
	v_lshlrev_b32_e32 v11, 2, v11
	ds_bpermute_b32 v11, v11, v14
	v_cmp_lt_i32_e64 s[38:39], 31, v47
	s_waitcnt lgkmcnt(0)
	s_nop 0
	v_cndmask_b32_e64 v11, 0, v11, s[38:39]
	v_add_u32_e32 v11, v11, v14
	v_cmp_eq_u32_e64 s[38:39], 63, v47
	s_and_saveexec_b64 s[86:87], s[38:39]
	v_mov_b32_e32 v14, s3
	ds_write_b32 v14, v11 offset:64
	s_or_b64 exec, exec, s[86:87]
	s_waitcnt lgkmcnt(0)
	s_barrier
	ds_read_b128 v[18:21], v46 offset:64
	ds_read_b128 v[22:25], v46 offset:80
	s_waitcnt lgkmcnt(0)
	s_barrier
	v_readfirstlane_b32 s33, v18
	v_readfirstlane_b32 s90, v19
	v_readfirstlane_b32 s89, v20
	v_readfirstlane_b32 s88, v21
	v_readfirstlane_b32 s87, v22
	v_readfirstlane_b32 s86, v23
	v_readfirstlane_b32 s85, v24
	v_readfirstlane_b32 s57, v25
	s_and_saveexec_b64 s[38:39], s[22:23]
	s_cbranch_execz .LBB0_2981
	s_and_b64 s[22:23], s[42:43], exec
	s_cselect_b32 s76, 0, s33
	s_add_i32 s33, s90, s33
	s_and_b64 s[22:23], s[46:47], exec
	s_cselect_b32 s77, s90, 0
	s_add_i32 s33, s33, s89
	s_and_b64 s[22:23], s[50:51], exec
	s_cselect_b32 s89, s89, 0
	s_add_i32 s33, s33, s88
	s_and_b64 s[22:23], s[58:59], exec
	s_cselect_b32 s88, s88, 0
	s_add_i32 s33, s33, s87
	s_and_b64 s[22:23], s[72:73], exec
	s_cselect_b32 s87, s87, 0
	s_add_i32 s33, s33, s86
	s_and_b64 s[22:23], s[78:79], exec
	s_cselect_b32 s86, s86, 0
	s_add_i32 s33, s33, s85
	s_and_b64 s[22:23], s[80:81], exec
	s_cselect_b32 s85, s85, 0
	s_add_i32 s33, s33, s57
	s_and_b64 s[22:23], s[82:83], exec
	s_cselect_b32 s22, s57, 0
	s_add_i32 s22, s22, s85
	s_add_i32 s22, s22, s86
	s_add_i32 s22, s22, s87
	s_add_i32 s22, s22, s88
	s_add_i32 s22, s22, s89
	s_add_i32 s22, s22, s77
	v_sub_u32_e32 v10, v11, v10
	s_add_i32 s22, s22, s76
	v_add_u32_e32 v18, s22, v10
	s_ashr_i32 s22, s33, 16
	s_sub_i32 s85, 0x200, s22
	s_ashr_i32 s86, s84, 4
	v_cmp_lt_i32_sdwa s[22:23], v18, s85 src0_sel:WORD_0 src1_sel:DWORD
	s_and_b32 s57, s84, 15
	s_and_b64 s[22:23], s[36:37], s[22:23]
	v_lshl_add_u32 v14, s86, 12, v42
	s_nor_b64 s[22:23], s[34:35], s[22:23]
	s_mul_i32 s101, s57, 0x8800
	v_add_u32_e32 v10, s101, v14
	s_and_saveexec_b64 s[76:77], s[22:23]
	s_xor_b64 s[22:23], exec, s[76:77]
	s_cbranch_execz .LBB0_2997
	v_ashrrev_i32_e32 v11, 31, v10
	v_lshl_add_u64 v[10:11], v[10:11], 2, s[64:65]
	global_store_dword v[10:11], v45, off

.LBB0_2999:
	s_or_b64 exec, exec, s[22:23]
	v_cndmask_b32_e64 v6, 0, 1, s[36:37]
	v_cndmask_b32_e64 v6, v6, 0, s[34:35]
	v_add_u32_sdwa v10, v18, v6 dst_sel:DWORD dst_unused:UNUSED_PAD src0_sel:WORD_0 src1_sel:DWORD
	v_cmp_gt_i32_e64 s[22:23], s85, v10
	s_and_b64 s[22:23], s[30:31], s[22:23]
	v_or_b32_e32 v11, 1, v14
	s_nor_b64 s[22:23], s[26:27], s[22:23]
	s_mul_i32 s101, s57, 0x8800
	v_add_u32_e32 v6, s101, v11
	s_and_saveexec_b64 s[30:31], s[22:23]
	s_xor_b64 s[22:23], exec, s[30:31]
	s_cbranch_execz .LBB0_3001
	v_ashrrev_i32_e32 v7, 31, v6
	v_lshl_add_u64 v[6:7], v[6:7], 2, s[64:65]
	global_store_dword v[6:7], v45, off

.LBB0_3003:
	s_or_b64 exec, exec, s[22:23]
	v_cndmask_b32_e64 v6, v17, 0, s[26:27]
	v_add_u32_e32 v10, v10, v6
	v_cmp_gt_i32_e64 s[22:23], s85, v10
	s_and_b64 s[22:23], s[28:29], s[22:23]
	v_or_b32_e32 v7, 2, v14
	s_nor_b64 s[22:23], s[24:25], s[22:23]
	s_mul_i32 s101, s57, 0x8800
	v_add_u32_e32 v6, s101, v7
	s_and_saveexec_b64 s[26:27], s[22:23]
	s_xor_b64 s[22:23], exec, s[26:27]
	s_cbranch_execz .LBB0_3005
	v_ashrrev_i32_e32 v7, 31, v6
	v_lshl_add_u64 v[6:7], v[6:7], 2, s[64:65]
	global_store_dword v[6:7], v45, off

.LBB0_3007:
	s_or_b64 exec, exec, s[22:23]
	v_cndmask_b32_e64 v6, v16, 0, s[24:25]
	v_add_u32_e32 v8, v10, v6
	v_cmp_gt_i32_e64 s[22:23], s85, v8
	s_and_b64 s[22:23], s[18:19], s[22:23]
	v_or_b32_e32 v7, 3, v14
	s_nor_b64 s[22:23], s[16:17], s[22:23]
	s_mul_i32 s101, s57, 0x8800
	v_add_u32_e32 v6, s101, v7
	s_and_saveexec_b64 s[24:25], s[22:23]
	s_xor_b64 s[22:23], exec, s[24:25]
	s_cbranch_execz .LBB0_3009
	v_ashrrev_i32_e32 v7, 31, v6
	v_lshl_add_u64 v[6:7], v[6:7], 2, s[64:65]
	global_store_dword v[6:7], v45, off

.LBB0_3011:
	s_or_b64 exec, exec, s[22:23]
	v_cndmask_b32_e64 v6, 0, 1, s[18:19]
	v_cndmask_b32_e64 v6, v6, 0, s[16:17]
	v_add_u32_e32 v8, v8, v6
	v_cmp_gt_i32_e64 s[16:17], s85, v8
	s_and_b64 s[16:17], s[20:21], s[16:17]
	v_or_b32_e32 v7, 4, v14
	s_nor_b64 s[16:17], s[14:15], s[16:17]
	s_mul_i32 s101, s57, 0x8800
	v_add_u32_e32 v6, s101, v7
	s_and_saveexec_b64 s[18:19], s[16:17]
	s_xor_b64 s[16:17], exec, s[18:19]
	s_cbranch_execz .LBB0_3013
	v_ashrrev_i32_e32 v7, 31, v6
	v_lshl_add_u64 v[6:7], v[6:7], 2, s[64:65]
	global_store_dword v[6:7], v45, off

.LBB0_3015:
	s_or_b64 exec, exec, s[16:17]
	v_cndmask_b32_e64 v2, v13, 0, s[14:15]
	v_add_u32_e32 v6, v8, v2
	v_cmp_gt_i32_e64 s[14:15], s85, v6
	s_and_b64 s[14:15], s[10:11], s[14:15]
	v_or_b32_e32 v7, 5, v14
	s_nor_b64 s[14:15], s[8:9], s[14:15]
	s_mul_i32 s101, s57, 0x8800
	v_add_u32_e32 v2, s101, v7
	s_and_saveexec_b64 s[16:17], s[14:15]
	s_xor_b64 s[14:15], exec, s[16:17]
	s_cbranch_execz .LBB0_3017
	v_ashrrev_i32_e32 v3, 31, v2
	v_lshl_add_u64 v[2:3], v[2:3], 2, s[64:65]
	global_store_dword v[2:3], v45, off

.LBB0_3019:
	s_or_b64 exec, exec, s[14:15]
	v_cndmask_b32_e64 v2, 0, 1, s[10:11]
	v_cndmask_b32_e64 v2, v2, 0, s[8:9]
	v_add_u32_e32 v6, v6, v2
	v_cmp_gt_i32_e64 s[8:9], s85, v6
	s_and_b64 s[8:9], s[12:13], s[8:9]
	v_or_b32_e32 v3, 6, v14
	s_nor_b64 s[8:9], vcc, s[8:9]
	s_mul_i32 s101, s57, 0x8800
	v_add_u32_e32 v2, s101, v3
	s_and_saveexec_b64 s[10:11], s[8:9]
	s_xor_b64 s[8:9], exec, s[10:11]
	s_cbranch_execz .LBB0_3021
	v_ashrrev_i32_e32 v3, 31, v2
	v_lshl_add_u64 v[2:3], v[2:3], 2, s[64:65]
	global_store_dword v[2:3], v45, off

.LBB0_3260:
	v_lshl_add_u32 v174, s54, 2, v179
	v_mul_u32_u24_e32 v4, 0x8800, v165
	v_add_u32_e32 v4, v4, v174
	v_ashrrev_i32_e32 v5, 31, v4
	v_lshl_add_u64 v[4:5], v[4:5], 2, s[64:65]
	global_load_dword v176, v[4:5], off
	v_mov_b32_e32 v177, 0
	s_waitcnt vmcnt(0)
	v_cmp_lt_i32_e32 vcc, -1, v176
	s_and_saveexec_b64 s[0:1], vcc
	s_cbranch_execz .LBB0_3262
	v_mov_b32_e32 v177, v2
	v_lshl_add_u64 v[4:5], v[176:177], 2, s[62:63]
	global_load_dword v177, v[4:5], off
